# v77 + P0 w_in copy item order: consecutive waves take adjacent column blocks of the same source rows (DRAM locality)
# speedup vs baseline: 1.0028x; 1.0028x over previous
.LBB0_58:
	s_mul_i32 s98, s11, 0xb60c
	s_lshr_b32 s98, s98, 24
	s_mul_i32 s99, s98, 0x168
	s_sub_i32 s8, s11, s99
	s_lshl_b32 s0, s8, 5
	s_cmp_gt_i32 s8, 63
	s_mov_b64 s[2:3], -1
	s_cbranch_scc1 .LBB0_62
	s_andn2_b64 vcc, exec, s[2:3]
	s_cbranch_vccz .LBB0_87

.LBB0_61:
	s_lshl_b32 s12, s98, 6
	s_nop 0
	s_and_b64 vcc, exec, s[2:3]
	s_cbranch_vccz .LBB0_21
	s_branch .LBB0_91

.LBB0_89:
	s_lshl_b32 s14, s3, 1
	s_lshl_b32 s13, s2, 1
	v_or_b32_e32 v12, s14, v0
	v_or_b32_e32 v14, s13, v1
	s_add_i32 s17, s14, 4
	s_add_i32 s19, s14, 8
	s_add_i32 s21, s14, 12
	s_add_i32 s23, s14, 16
	s_add_i32 s25, s14, 20
	s_add_i32 s27, s14, 24
	s_add_i32 s28, s14, 28
	v_mad_u64_u32 v[12:13], s[14:15], v12, s5, v[2:3]
	s_add_i32 s3, s3, 16
	s_add_i32 s2, s2, 16
	s_add_i32 s12, s12, -16
	s_add_i32 s16, s13, 4
	s_add_i32 s18, s13, 8
	s_add_i32 s20, s13, 12
	s_add_i32 s22, s13, 16
	s_add_i32 s24, s13, 20
	s_add_i32 s26, s13, 24
	s_add_i32 s13, s13, 28
	v_mad_u64_u32 v[14:15], s[14:15], v14, s5, v[2:3]
	v_or_b32_e32 v13, s17, v0
	v_or_b32_e32 v15, s16, v1
	v_or_b32_e32 v18, s18, v1
	v_or_b32_e32 v16, s19, v0
	v_or_b32_e32 v22, s20, v1
	v_or_b32_e32 v20, s21, v0
	v_or_b32_e32 v26, s22, v1
	v_or_b32_e32 v24, s23, v0
	v_or_b32_e32 v50, s24, v1
	v_or_b32_e32 v28, s25, v0
	v_or_b32_e32 v54, s26, v1
	v_or_b32_e32 v52, s27, v0
	v_or_b32_e32 v58, s13, v1
	v_or_b32_e32 v56, s28, v0
	s_cmp_eq_u32 s12, 0
	ds_write_b32 v12, v5
	ds_write_b32 v14, v5
	v_mad_u64_u32 v[12:13], s[14:15], v13, s5, v[2:3]
	v_mad_u64_u32 v[14:15], s[14:15], v15, s5, v[2:3]
	v_mad_u64_u32 v[16:17], s[14:15], v16, s5, v[2:3]
	v_mad_u64_u32 v[18:19], s[14:15], v18, s5, v[2:3]
	v_mad_u64_u32 v[20:21], s[14:15], v20, s5, v[2:3]
	v_mad_u64_u32 v[22:23], s[14:15], v22, s5, v[2:3]
	v_mad_u64_u32 v[24:25], s[14:15], v24, s5, v[2:3]
	v_mad_u64_u32 v[26:27], s[14:15], v26, s5, v[2:3]
	v_mad_u64_u32 v[28:29], s[14:15], v28, s5, v[2:3]
	v_mad_u64_u32 v[50:51], s[14:15], v50, s5, v[2:3]
	v_mad_u64_u32 v[52:53], s[14:15], v52, s5, v[2:3]
	v_mad_u64_u32 v[54:55], s[14:15], v54, s5, v[2:3]
	v_mad_u64_u32 v[56:57], s[14:15], v56, s5, v[2:3]
	v_mad_u64_u32 v[58:59], s[14:15], v58, s5, v[2:3]
	ds_write_b32 v12, v5
	ds_write_b32 v14, v5
	ds_write_b32 v16, v5
	ds_write_b32 v18, v5
	ds_write_b32 v20, v5
	ds_write_b32 v22, v5
	ds_write_b32 v24, v5
	ds_write_b32 v26, v5
	ds_write_b32 v28, v5
	ds_write_b32 v50, v5
	ds_write_b32 v52, v5
	ds_write_b32 v54, v5
	ds_write_b32 v56, v5
	ds_write_b32 v58, v5
	s_cbranch_scc0 .LBB0_89
	s_lshl_b32 s12, s98, 6
	s_nop 0
	s_branch .LBB0_21
